# S5 pass-2: 4-fma recurrence steps, packed-f32 gelu, and the gelu of a chunk interleaved into the next chunk's recurrence steps
# speedup vs baseline: 1.0034x; 1.0034x over previous
.LBB0_873:
	v_mov_b32_e32 v224, 0x3d122279
	v_mov_b32_e32 v225, 0x3d122279
	v_mov_b32_e32 v226, 0x3f4c422a
	v_mov_b32_e32 v227, 0x3f4c422a
	v_mov_b32_e32 v228, 0xc038aa3b
	v_mov_b32_e32 v229, 0xc038aa3b
	v_mov_b32_e32 v230, 1.0
	v_mov_b32_e32 v231, 1.0
	v_cndmask_b32_e64 v93, v83, 0, s[10:11]
	v_cndmask_b32_e64 v92, v82, 0, s[10:11]
	v_cndmask_b32_e64 v91, v81, 0, s[10:11]
	v_cndmask_b32_e64 v90, v80, 0, s[10:11]
	v_add_u32_e32 v81, v139, v141
	v_add_u32_e32 v83, v139, v142
	v_mfma_f32_16x16x32_bf16 v[192:195], v[90:93], v[0:3], 0
	v_add_u32_e32 v88, v139, v143
	v_add_u32_e32 v82, s86, v140
	v_mov_b32_e32 v240, v86
	v_mov_b32_e32 v241, v87
	v_mfma_f32_16x16x32_bf16 v[196:199], v[90:93], v[4:7], 0
	v_mfma_f32_16x16x32_bf16 v[200:203], v[90:93], v[8:11], 0
	s_nop 2
	s_nop 2
	v_cndmask_b32_e64 v79, v79, 0, s[10:11]
	v_mfma_f32_16x16x32_bf16 v[204:207], v[90:93], v[12:15], 0
	v_cndmask_b32_e64 v78, v78, 0, s[10:11]
	v_cndmask_b32_e64 v77, v77, 0, s[10:11]
	v_cndmask_b32_e64 v76, v76, 0, s[10:11]
	v_mfma_f32_16x16x32_bf16 v[212:215], v[90:93], v[20:23], 0
	v_cndmask_b32_e64 v75, v75, 0, s[10:11]
	v_cndmask_b32_e64 v74, v74, 0, s[10:11]
	v_cndmask_b32_e64 v73, v73, 0, s[10:11]
	v_mfma_f32_16x16x32_bf16 v[208:211], v[90:93], v[16:19], 0
	s_nop 6
	v_mfma_f32_16x16x32_bf16 v[216:219], v[90:93], v[24:27], 0
	s_nop 6
	v_mfma_f32_16x16x32_bf16 v[220:223], v[90:93], v[28:31], 0
	v_cndmask_b32_e64 v72, v72, 0, s[10:11]
	v_cndmask_b32_e64 v71, v71, 0, s[10:11]
	v_cndmask_b32_e64 v70, v70, 0, s[10:11]
	v_mfma_f32_16x16x32_bf16 v[90:93], v[90:93], v[48:51], 0
	v_cndmask_b32_e64 v69, v69, 0, s[10:11]
	s_nop 2
	s_nop 7
	v_permlane16_swap_b32_e32 v192, v196
	v_permlane16_swap_b32_e32 v193, v197
	v_permlane16_swap_b32_e32 v194, v198
	v_permlane16_swap_b32_e32 v195, v199
	v_permlane16_swap_b32_e32 v200, v204
	v_permlane16_swap_b32_e32 v201, v205
	v_permlane16_swap_b32_e32 v202, v206
	v_permlane16_swap_b32_e32 v203, v207
	v_permlane16_swap_b32_e32 v208, v212
	v_permlane16_swap_b32_e32 v209, v213
	v_permlane16_swap_b32_e32 v210, v214
	v_permlane16_swap_b32_e32 v211, v215
	v_permlane16_swap_b32_e32 v216, v220
	v_permlane16_swap_b32_e32 v217, v221
	v_permlane16_swap_b32_e32 v218, v222
	v_permlane16_swap_b32_e32 v219, v223
	v_permlane32_swap_b32_e32 v192, v200
	v_permlane32_swap_b32_e32 v193, v201
	v_permlane32_swap_b32_e32 v194, v202
	v_permlane32_swap_b32_e32 v195, v203
	v_permlane32_swap_b32_e32 v196, v204
	v_permlane32_swap_b32_e32 v197, v205
	v_permlane32_swap_b32_e32 v198, v206
	v_permlane32_swap_b32_e32 v199, v207
	v_permlane32_swap_b32_e32 v208, v216
	v_permlane32_swap_b32_e32 v209, v217
	v_permlane32_swap_b32_e32 v210, v218
	v_permlane32_swap_b32_e32 v211, v219
	v_permlane32_swap_b32_e32 v212, v220
	v_permlane32_swap_b32_e32 v213, v221
	v_permlane32_swap_b32_e32 v214, v222
	v_permlane32_swap_b32_e32 v215, v223
	v_fma_f32 v242, -v132, v241, v192
	v_fma_f32 v243, v132, v240, v208
	v_fma_f32 v244, v128, v240, v242
	v_fma_f32 v245, v128, v241, v243
	v_cvt_pk_bf16_f32 v248, v244, v245
	ds_write_b32 v149, v248 offset:10240
	v_fma_f32 v242, -v132, v245, v193
	v_fma_f32 v243, v132, v244, v209
	v_fma_f32 v246, v128, v244, v242
	v_fma_f32 v247, v128, v245, v243
	v_cvt_pk_bf16_f32 v249, v246, v247
	ds_write_b32 v149, v249 offset:10512
	v_fma_f32 v242, -v132, v247, v194
	v_fma_f32 v243, v132, v246, v210
	v_fma_f32 v244, v128, v246, v242
	v_fma_f32 v245, v128, v247, v243
	v_cvt_pk_bf16_f32 v248, v244, v245
	ds_write_b32 v149, v248 offset:10784
	v_fma_f32 v242, -v132, v245, v195
	v_fma_f32 v243, v132, v244, v211
	v_fma_f32 v246, v128, v244, v242
	v_fma_f32 v247, v128, v245, v243
	v_cvt_pk_bf16_f32 v249, v246, v247
	ds_write_b32 v149, v249 offset:11056
	v_fma_f32 v242, -v132, v247, v196
	v_fma_f32 v243, v132, v246, v212
	v_fma_f32 v244, v128, v246, v242
	v_fma_f32 v245, v128, v247, v243
	v_cvt_pk_bf16_f32 v248, v244, v245
	ds_write_b32 v149, v248 offset:11328
	v_fma_f32 v242, -v132, v245, v197
	v_fma_f32 v243, v132, v244, v213
	v_fma_f32 v246, v128, v244, v242
	v_fma_f32 v247, v128, v245, v243
	v_cvt_pk_bf16_f32 v249, v246, v247
	ds_write_b32 v149, v249 offset:11600
	v_fma_f32 v242, -v132, v247, v198
	v_fma_f32 v243, v132, v246, v214
	v_fma_f32 v244, v128, v246, v242
	v_fma_f32 v245, v128, v247, v243
	v_cvt_pk_bf16_f32 v248, v244, v245
	ds_write_b32 v149, v248 offset:11872
	v_fma_f32 v242, -v132, v245, v199
	v_fma_f32 v243, v132, v244, v215
	v_fma_f32 v246, v128, v244, v242
	v_fma_f32 v247, v128, v245, v243
	v_cvt_pk_bf16_f32 v249, v246, v247
	ds_write_b32 v149, v249 offset:12144
	v_fma_f32 v242, -v132, v247, v200
	v_fma_f32 v243, v132, v246, v216
	v_fma_f32 v244, v128, v246, v242
	v_fma_f32 v245, v128, v247, v243
	v_cvt_pk_bf16_f32 v248, v244, v245
	ds_write_b32 v149, v248 offset:12416
	v_fma_f32 v242, -v132, v245, v201
	v_fma_f32 v243, v132, v244, v217
	v_fma_f32 v246, v128, v244, v242
	v_fma_f32 v247, v128, v245, v243
	v_cvt_pk_bf16_f32 v249, v246, v247
	ds_write_b32 v149, v249 offset:12688
	v_fma_f32 v242, -v132, v247, v202
	v_fma_f32 v243, v132, v246, v218
	v_fma_f32 v244, v128, v246, v242
	v_fma_f32 v245, v128, v247, v243
	v_cvt_pk_bf16_f32 v248, v244, v245
	ds_write_b32 v149, v248 offset:12960
	v_fma_f32 v242, -v132, v245, v203
	v_fma_f32 v243, v132, v244, v219
	v_fma_f32 v246, v128, v244, v242
	v_fma_f32 v247, v128, v245, v243
	v_cvt_pk_bf16_f32 v249, v246, v247
	ds_write_b32 v149, v249 offset:13232
	v_fma_f32 v242, -v132, v247, v204
	v_fma_f32 v243, v132, v246, v220
	v_fma_f32 v244, v128, v246, v242
	v_fma_f32 v245, v128, v247, v243
	v_cvt_pk_bf16_f32 v248, v244, v245
	ds_write_b32 v149, v248 offset:13504
	v_fma_f32 v242, -v132, v245, v205
	v_fma_f32 v243, v132, v244, v221
	v_fma_f32 v246, v128, v244, v242
	v_fma_f32 v247, v128, v245, v243
	v_cvt_pk_bf16_f32 v249, v246, v247
	ds_write_b32 v149, v249 offset:13776
	v_fma_f32 v242, -v132, v247, v206
	v_fma_f32 v243, v132, v246, v222
	v_fma_f32 v244, v128, v246, v242
	v_fma_f32 v245, v128, v247, v243
	v_cvt_pk_bf16_f32 v248, v244, v245
	ds_write_b32 v149, v248 offset:14048
	v_fma_f32 v242, -v132, v245, v207
	v_fma_f32 v243, v132, v244, v223
	v_fma_f32 v87, v128, v244, v242
	v_fma_f32 v86, v128, v245, v243
	v_cvt_pk_bf16_f32 v249, v87, v86
	ds_write_b32 v149, v249 offset:14320
	s_waitcnt lgkmcnt(0)
	v_add_u32_e32 v80, v150, v138
	ds_read_b128 v[94:97], v80 offset:10240
	ds_read_b128 v[98:101], v80 offset:10304
	ds_read_b128 v[184:187], v80 offset:10368
	ds_read_b128 v[188:191], v80 offset:10432
	s_waitcnt lgkmcnt(3)
	v_mfma_f32_16x16x32_bf16 v[90:93], v[94:97], v[32:35], v[90:93]
	v_cndmask_b32_e64 v68, v68, 0, s[10:11]
	s_add_u32 s30, s30, 0x40000
	s_waitcnt lgkmcnt(2)
	v_mfma_f32_16x16x32_bf16 v[90:93], v[98:101], v[36:39], v[90:93]
	s_addc_u32 s31, s31, 0
	s_cmp_eq_u32 s30, 0x240000
	s_waitcnt lgkmcnt(1)
	v_mfma_f32_16x16x32_bf16 v[90:93], v[184:187], v[40:43], v[90:93]
	s_cselect_b64 s[34:35], -1, 0
	s_waitcnt lgkmcnt(0)
	v_mfma_f32_16x16x32_bf16 v[90:93], v[188:191], v[44:47], v[90:93]
	v_mfma_f32_16x16x32_bf16 v[196:199], v[76:79], v[4:7], 0
	v_mfma_f32_16x16x32_bf16 v[200:203], v[76:79], v[8:11], 0
	s_nop 5
	v_mfma_f32_16x16x32_bf16 v[204:207], v[76:79], v[12:15], 0
	v_mfma_f32_16x16x32_bf16 v[192:195], v[76:79], v[0:3], 0
	v_mfma_f32_16x16x32_bf16 v[208:211], v[76:79], v[16:19], 0
	s_nop 0
	s_nop 3
	v_mfma_f32_16x16x32_bf16 v[212:215], v[76:79], v[20:23], 0
	v_mov_b32_e32 v240, v87
	v_mov_b32_e32 v241, v86
	v_mfma_f32_16x16x32_bf16 v[216:219], v[76:79], v[24:27], 0
	s_nop 0
	s_nop 4
	v_mfma_f32_16x16x32_bf16 v[220:223], v[76:79], v[28:31], 0
	v_mfma_f32_16x16x32_bf16 v[76:79], v[76:79], v[48:51], 0
	s_nop 5
	s_nop 7
	v_permlane16_swap_b32_e32 v192, v196
	v_permlane16_swap_b32_e32 v193, v197
	v_permlane16_swap_b32_e32 v194, v198
	v_permlane16_swap_b32_e32 v195, v199
	v_permlane16_swap_b32_e32 v200, v204
	v_permlane16_swap_b32_e32 v201, v205
	v_permlane16_swap_b32_e32 v202, v206
	v_permlane16_swap_b32_e32 v203, v207
	v_permlane16_swap_b32_e32 v208, v212
	v_permlane16_swap_b32_e32 v209, v213
	v_permlane16_swap_b32_e32 v210, v214
	v_permlane16_swap_b32_e32 v211, v215
	v_permlane16_swap_b32_e32 v216, v220
	v_permlane16_swap_b32_e32 v217, v221
	v_permlane16_swap_b32_e32 v218, v222
	v_permlane16_swap_b32_e32 v219, v223
	v_permlane32_swap_b32_e32 v192, v200
	v_permlane32_swap_b32_e32 v193, v201
	v_permlane32_swap_b32_e32 v194, v202
	v_permlane32_swap_b32_e32 v195, v203
	v_permlane32_swap_b32_e32 v196, v204
	v_permlane32_swap_b32_e32 v197, v205
	v_permlane32_swap_b32_e32 v198, v206
	v_permlane32_swap_b32_e32 v199, v207
	v_permlane32_swap_b32_e32 v208, v216
	v_permlane32_swap_b32_e32 v209, v217
	v_permlane32_swap_b32_e32 v210, v218
	v_permlane32_swap_b32_e32 v211, v219
	v_permlane32_swap_b32_e32 v212, v220
	v_permlane32_swap_b32_e32 v213, v221
	v_permlane32_swap_b32_e32 v214, v222
	v_permlane32_swap_b32_e32 v215, v223
	v_fma_f32 v242, -v132, v241, v192
	v_fma_f32 v243, v132, v240, v208
	v_fma_f32 v244, v128, v240, v242
	v_fma_f32 v245, v128, v241, v243
	v_cvt_pk_bf16_f32 v248, v244, v245
	ds_write_b32 v149, v248 offset:10240
	v_pk_mul_f32 v[232:233], v[90:91], v[224:225]
	v_pk_mul_f32 v[234:235], v[92:93], v[224:225]
	v_fma_f32 v242, -v132, v245, v193
	v_fma_f32 v243, v132, v244, v209
	v_fma_f32 v246, v128, v244, v242
	v_fma_f32 v247, v128, v245, v243
	v_cvt_pk_bf16_f32 v249, v246, v247
	ds_write_b32 v149, v249 offset:10512
	v_pk_fma_f32 v[232:233], v[90:91], v[232:233], v[226:227]
	v_pk_fma_f32 v[234:235], v[92:93], v[234:235], v[226:227]
	v_fma_f32 v242, -v132, v247, v194
	v_fma_f32 v243, v132, v246, v210
	v_fma_f32 v244, v128, v246, v242
	v_fma_f32 v245, v128, v247, v243
	v_cvt_pk_bf16_f32 v248, v244, v245
	ds_write_b32 v149, v248 offset:10784
	v_pk_mul_f32 v[232:233], v[90:91], v[232:233]
	v_pk_mul_f32 v[234:235], v[92:93], v[234:235]
	v_fma_f32 v242, -v132, v245, v195
	v_fma_f32 v243, v132, v244, v211
	v_fma_f32 v246, v128, v244, v242
	v_fma_f32 v247, v128, v245, v243
	v_cvt_pk_bf16_f32 v249, v246, v247
	ds_write_b32 v149, v249 offset:11056
	v_pk_mul_f32 v[232:233], v[232:233], v[228:229]
	v_pk_mul_f32 v[234:235], v[234:235], v[228:229]
	v_fma_f32 v242, -v132, v247, v196
	v_fma_f32 v243, v132, v246, v212
	v_fma_f32 v244, v128, v246, v242
	v_fma_f32 v245, v128, v247, v243
	v_cvt_pk_bf16_f32 v248, v244, v245
	ds_write_b32 v149, v248 offset:11328
	v_exp_f32_e32 v232, v232
	v_exp_f32_e32 v233, v233
	v_fma_f32 v242, -v132, v245, v197
	v_fma_f32 v243, v132, v244, v213
	v_fma_f32 v246, v128, v244, v242
	v_fma_f32 v247, v128, v245, v243
	v_cvt_pk_bf16_f32 v249, v246, v247
	ds_write_b32 v149, v249 offset:11600
	v_exp_f32_e32 v234, v234
	v_exp_f32_e32 v235, v235
	v_fma_f32 v242, -v132, v247, v198
	v_fma_f32 v243, v132, v246, v214
	v_fma_f32 v244, v128, v246, v242
	v_fma_f32 v245, v128, v247, v243
	v_cvt_pk_bf16_f32 v248, v244, v245
	ds_write_b32 v149, v248 offset:11872
	v_pk_add_f32 v[232:233], v[232:233], v[230:231]
	v_pk_add_f32 v[234:235], v[234:235], v[230:231]
	v_fma_f32 v242, -v132, v245, v199
	v_fma_f32 v243, v132, v244, v215
	v_fma_f32 v246, v128, v244, v242
	v_fma_f32 v247, v128, v245, v243
	v_cvt_pk_bf16_f32 v249, v246, v247
	ds_write_b32 v149, v249 offset:12144
	v_rcp_f32_e32 v232, v232
	v_rcp_f32_e32 v233, v233
	v_fma_f32 v242, -v132, v247, v200
	v_fma_f32 v243, v132, v246, v216
	v_fma_f32 v244, v128, v246, v242
	v_fma_f32 v245, v128, v247, v243
	v_cvt_pk_bf16_f32 v248, v244, v245
	ds_write_b32 v149, v248 offset:12416
	v_rcp_f32_e32 v234, v234
	v_rcp_f32_e32 v235, v235
	v_fma_f32 v242, -v132, v245, v201
	v_fma_f32 v243, v132, v244, v217
	v_fma_f32 v246, v128, v244, v242
	v_fma_f32 v247, v128, v245, v243
	v_cvt_pk_bf16_f32 v249, v246, v247
	ds_write_b32 v149, v249 offset:12688
	v_pk_mul_f32 v[232:233], v[90:91], v[232:233]
	v_pk_mul_f32 v[234:235], v[92:93], v[234:235]
	v_fma_f32 v242, -v132, v247, v202
	v_fma_f32 v243, v132, v246, v218
	v_fma_f32 v244, v128, v246, v242
	v_fma_f32 v245, v128, v247, v243
	v_cvt_pk_bf16_f32 v248, v244, v245
	ds_write_b32 v149, v248 offset:12960
	v_cvt_pk_bf16_f32 v236, v232, v232
	v_cvt_pk_bf16_f32 v237, v233, v233
	v_fma_f32 v242, -v132, v245, v203
	v_fma_f32 v243, v132, v244, v219
	v_fma_f32 v246, v128, v244, v242
	v_fma_f32 v247, v128, v245, v243
	v_cvt_pk_bf16_f32 v249, v246, v247
	ds_write_b32 v149, v249 offset:13232
	v_cvt_pk_bf16_f32 v238, v234, v234
	v_cvt_pk_bf16_f32 v239, v235, v235
	v_fma_f32 v242, -v132, v247, v204
	v_fma_f32 v243, v132, v246, v220
	v_fma_f32 v244, v128, v246, v242
	v_fma_f32 v245, v128, v247, v243
	v_cvt_pk_bf16_f32 v248, v244, v245
	ds_write_b32 v149, v248 offset:13504
	ds_write_b16 v160, v236 offset:14592
	ds_write_b16 v160, v237 offset:14624
	v_fma_f32 v242, -v132, v245, v205
	v_fma_f32 v243, v132, v244, v221
	v_fma_f32 v246, v128, v244, v242
	v_fma_f32 v247, v128, v245, v243
	v_cvt_pk_bf16_f32 v249, v246, v247
	ds_write_b32 v149, v249 offset:13776
	ds_write_b16 v160, v238 offset:14656
	ds_write_b16 v161, v239 offset:14592
	v_fma_f32 v242, -v132, v247, v206
	v_fma_f32 v243, v132, v246, v222
	v_fma_f32 v244, v128, v246, v242
	v_fma_f32 v245, v128, v247, v243
	v_cvt_pk_bf16_f32 v248, v244, v245
	ds_write_b32 v149, v248 offset:14048
	v_fma_f32 v242, -v132, v245, v207
	v_fma_f32 v243, v132, v244, v223
	v_fma_f32 v87, v128, v244, v242
	v_fma_f32 v86, v128, v245, v243
	v_cvt_pk_bf16_f32 v249, v87, v86
	ds_write_b32 v149, v249 offset:14320
	s_waitcnt lgkmcnt(0)
	ds_read_b128 v[90:93], v80 offset:10240
	ds_read_b128 v[94:97], v80 offset:10304
	ds_read_b128 v[184:187], v80 offset:10368
	ds_read_b128 v[188:191], v80 offset:10432
	s_waitcnt lgkmcnt(3)
	v_mfma_f32_16x16x32_bf16 v[76:79], v[90:93], v[32:35], v[76:79]
	s_waitcnt lgkmcnt(2)
	v_mfma_f32_16x16x32_bf16 v[76:79], v[94:97], v[36:39], v[76:79]
	s_waitcnt lgkmcnt(1)
	v_mfma_f32_16x16x32_bf16 v[76:79], v[184:187], v[40:43], v[76:79]
	s_waitcnt lgkmcnt(0)
	v_mfma_f32_16x16x32_bf16 v[76:79], v[188:191], v[44:47], v[76:79]
	v_mfma_f32_16x16x32_bf16 v[196:199], v[72:75], v[4:7], 0
	v_mfma_f32_16x16x32_bf16 v[200:203], v[72:75], v[8:11], 0
	s_nop 5
	v_mfma_f32_16x16x32_bf16 v[204:207], v[72:75], v[12:15], 0
	v_mfma_f32_16x16x32_bf16 v[192:195], v[72:75], v[0:3], 0
	v_mfma_f32_16x16x32_bf16 v[208:211], v[72:75], v[16:19], 0
	s_nop 0
	s_nop 3
	v_mfma_f32_16x16x32_bf16 v[212:215], v[72:75], v[20:23], 0
	v_mov_b32_e32 v240, v87
	v_mov_b32_e32 v241, v86
	v_mfma_f32_16x16x32_bf16 v[216:219], v[72:75], v[24:27], 0
	s_nop 0
	s_nop 4
	v_mfma_f32_16x16x32_bf16 v[220:223], v[72:75], v[28:31], 0
	v_mfma_f32_16x16x32_bf16 v[72:75], v[72:75], v[48:51], 0
	s_nop 5
	s_nop 7
	v_permlane16_swap_b32_e32 v192, v196
	v_permlane16_swap_b32_e32 v193, v197
	v_permlane16_swap_b32_e32 v194, v198
	v_permlane16_swap_b32_e32 v195, v199
	v_permlane16_swap_b32_e32 v200, v204
	v_permlane16_swap_b32_e32 v201, v205
	v_permlane16_swap_b32_e32 v202, v206
	v_permlane16_swap_b32_e32 v203, v207
	v_permlane16_swap_b32_e32 v208, v212
	v_permlane16_swap_b32_e32 v209, v213
	v_permlane16_swap_b32_e32 v210, v214
	v_permlane16_swap_b32_e32 v211, v215
	v_permlane16_swap_b32_e32 v216, v220
	v_permlane16_swap_b32_e32 v217, v221
	v_permlane16_swap_b32_e32 v218, v222
	v_permlane16_swap_b32_e32 v219, v223
	v_permlane32_swap_b32_e32 v192, v200
	v_permlane32_swap_b32_e32 v193, v201
	v_permlane32_swap_b32_e32 v194, v202
	v_permlane32_swap_b32_e32 v195, v203
	v_permlane32_swap_b32_e32 v196, v204
	v_permlane32_swap_b32_e32 v197, v205
	v_permlane32_swap_b32_e32 v198, v206
	v_permlane32_swap_b32_e32 v199, v207
	v_permlane32_swap_b32_e32 v208, v216
	v_permlane32_swap_b32_e32 v209, v217
	v_permlane32_swap_b32_e32 v210, v218
	v_permlane32_swap_b32_e32 v211, v219
	v_permlane32_swap_b32_e32 v212, v220
	v_permlane32_swap_b32_e32 v213, v221
	v_permlane32_swap_b32_e32 v214, v222
	v_permlane32_swap_b32_e32 v215, v223
	v_fma_f32 v242, -v132, v241, v192
	v_fma_f32 v243, v132, v240, v208
	v_fma_f32 v244, v128, v240, v242
	v_fma_f32 v245, v128, v241, v243
	v_cvt_pk_bf16_f32 v248, v244, v245
	ds_write_b32 v149, v248 offset:10240
	v_pk_mul_f32 v[232:233], v[76:77], v[224:225]
	v_pk_mul_f32 v[234:235], v[78:79], v[224:225]
	v_fma_f32 v242, -v132, v245, v193
	v_fma_f32 v243, v132, v244, v209
	v_fma_f32 v246, v128, v244, v242
	v_fma_f32 v247, v128, v245, v243
	v_cvt_pk_bf16_f32 v249, v246, v247
	ds_write_b32 v149, v249 offset:10512
	v_pk_fma_f32 v[232:233], v[76:77], v[232:233], v[226:227]
	v_pk_fma_f32 v[234:235], v[78:79], v[234:235], v[226:227]
	v_fma_f32 v242, -v132, v247, v194
	v_fma_f32 v243, v132, v246, v210
	v_fma_f32 v244, v128, v246, v242
	v_fma_f32 v245, v128, v247, v243
	v_cvt_pk_bf16_f32 v248, v244, v245
	ds_write_b32 v149, v248 offset:10784
	v_pk_mul_f32 v[232:233], v[76:77], v[232:233]
	v_pk_mul_f32 v[234:235], v[78:79], v[234:235]
	v_fma_f32 v242, -v132, v245, v195
	v_fma_f32 v243, v132, v244, v211
	v_fma_f32 v246, v128, v244, v242
	v_fma_f32 v247, v128, v245, v243
	v_cvt_pk_bf16_f32 v249, v246, v247
	ds_write_b32 v149, v249 offset:11056
	v_pk_mul_f32 v[232:233], v[232:233], v[228:229]
	v_pk_mul_f32 v[234:235], v[234:235], v[228:229]
	v_fma_f32 v242, -v132, v247, v196
	v_fma_f32 v243, v132, v246, v212
	v_fma_f32 v244, v128, v246, v242
	v_fma_f32 v245, v128, v247, v243
	v_cvt_pk_bf16_f32 v248, v244, v245
	ds_write_b32 v149, v248 offset:11328
	v_exp_f32_e32 v232, v232
	v_exp_f32_e32 v233, v233
	v_fma_f32 v242, -v132, v245, v197
	v_fma_f32 v243, v132, v244, v213
	v_fma_f32 v246, v128, v244, v242
	v_fma_f32 v247, v128, v245, v243
	v_cvt_pk_bf16_f32 v249, v246, v247
	ds_write_b32 v149, v249 offset:11600
	v_exp_f32_e32 v234, v234
	v_exp_f32_e32 v235, v235
	v_fma_f32 v242, -v132, v247, v198
	v_fma_f32 v243, v132, v246, v214
	v_fma_f32 v244, v128, v246, v242
	v_fma_f32 v245, v128, v247, v243
	v_cvt_pk_bf16_f32 v248, v244, v245
	ds_write_b32 v149, v248 offset:11872
	v_pk_add_f32 v[232:233], v[232:233], v[230:231]
	v_pk_add_f32 v[234:235], v[234:235], v[230:231]
	v_fma_f32 v242, -v132, v245, v199
	v_fma_f32 v243, v132, v244, v215
	v_fma_f32 v246, v128, v244, v242
	v_fma_f32 v247, v128, v245, v243
	v_cvt_pk_bf16_f32 v249, v246, v247
	ds_write_b32 v149, v249 offset:12144
	v_rcp_f32_e32 v232, v232
	v_rcp_f32_e32 v233, v233
	v_fma_f32 v242, -v132, v247, v200
	v_fma_f32 v243, v132, v246, v216
	v_fma_f32 v244, v128, v246, v242
	v_fma_f32 v245, v128, v247, v243
	v_cvt_pk_bf16_f32 v248, v244, v245
	ds_write_b32 v149, v248 offset:12416
	v_rcp_f32_e32 v234, v234
	v_rcp_f32_e32 v235, v235
	v_fma_f32 v242, -v132, v245, v201
	v_fma_f32 v243, v132, v244, v217
	v_fma_f32 v246, v128, v244, v242
	v_fma_f32 v247, v128, v245, v243
	v_cvt_pk_bf16_f32 v249, v246, v247
	ds_write_b32 v149, v249 offset:12688
	v_pk_mul_f32 v[232:233], v[76:77], v[232:233]
	v_pk_mul_f32 v[234:235], v[78:79], v[234:235]
	v_fma_f32 v242, -v132, v247, v202
	v_fma_f32 v243, v132, v246, v218
	v_fma_f32 v244, v128, v246, v242
	v_fma_f32 v245, v128, v247, v243
	v_cvt_pk_bf16_f32 v248, v244, v245
	ds_write_b32 v149, v248 offset:12960
	v_cvt_pk_bf16_f32 v236, v232, v232
	v_cvt_pk_bf16_f32 v237, v233, v233
	v_fma_f32 v242, -v132, v245, v203
	v_fma_f32 v243, v132, v244, v219
	v_fma_f32 v246, v128, v244, v242
	v_fma_f32 v247, v128, v245, v243
	v_cvt_pk_bf16_f32 v249, v246, v247
	ds_write_b32 v149, v249 offset:13232
	v_cvt_pk_bf16_f32 v238, v234, v234
	v_cvt_pk_bf16_f32 v239, v235, v235
	v_fma_f32 v242, -v132, v247, v204
	v_fma_f32 v243, v132, v246, v220
	v_fma_f32 v244, v128, v246, v242
	v_fma_f32 v245, v128, v247, v243
	v_cvt_pk_bf16_f32 v248, v244, v245
	ds_write_b32 v149, v248 offset:13504
	ds_write_b16 v160, v236 offset:15104
	ds_write_b16 v160, v237 offset:15136
	v_fma_f32 v242, -v132, v245, v205
	v_fma_f32 v243, v132, v244, v221
	v_fma_f32 v246, v128, v244, v242
	v_fma_f32 v247, v128, v245, v243
	v_cvt_pk_bf16_f32 v249, v246, v247
	ds_write_b32 v149, v249 offset:13776
	ds_write_b16 v160, v238 offset:15168
	ds_write_b16 v162, v239 offset:14592
	v_fma_f32 v242, -v132, v247, v206
	v_fma_f32 v243, v132, v246, v222
	v_fma_f32 v244, v128, v246, v242
	v_fma_f32 v245, v128, v247, v243
	v_cvt_pk_bf16_f32 v248, v244, v245
	ds_write_b32 v149, v248 offset:14048
	v_fma_f32 v242, -v132, v245, v207
	v_fma_f32 v243, v132, v244, v223
	v_fma_f32 v110, v128, v244, v242
	v_fma_f32 v111, v128, v245, v243
	v_cvt_pk_bf16_f32 v249, v110, v111
	ds_write_b32 v149, v249 offset:14320
	s_waitcnt lgkmcnt(0)
	ds_read_b128 v[76:79], v80 offset:10240
	ds_read_b128 v[90:93], v80 offset:10304
	ds_read_b128 v[184:187], v80 offset:10368
	ds_read_b128 v[188:191], v80 offset:10432
	s_waitcnt lgkmcnt(3)
	v_mfma_f32_16x16x32_bf16 v[72:75], v[76:79], v[32:35], v[72:75]
	s_waitcnt lgkmcnt(2)
	v_mfma_f32_16x16x32_bf16 v[72:75], v[90:93], v[36:39], v[72:75]
	s_waitcnt lgkmcnt(1)
	v_mfma_f32_16x16x32_bf16 v[72:75], v[184:187], v[40:43], v[72:75]
	s_waitcnt lgkmcnt(0)
	v_mfma_f32_16x16x32_bf16 v[72:75], v[188:191], v[44:47], v[72:75]
	v_mfma_f32_16x16x32_bf16 v[196:199], v[68:71], v[4:7], 0
	v_mfma_f32_16x16x32_bf16 v[200:203], v[68:71], v[8:11], 0
	s_nop 5
	v_mfma_f32_16x16x32_bf16 v[204:207], v[68:71], v[12:15], 0
	v_mfma_f32_16x16x32_bf16 v[192:195], v[68:71], v[0:3], 0
	v_mfma_f32_16x16x32_bf16 v[208:211], v[68:71], v[16:19], 0
	s_nop 0
	s_nop 3
	v_mfma_f32_16x16x32_bf16 v[212:215], v[68:71], v[20:23], 0
	v_mfma_f32_16x16x32_bf16 v[216:219], v[68:71], v[24:27], 0
	s_nop 2
	s_nop 2
	v_mov_b32_e32 v240, v110
	v_mov_b32_e32 v241, v111
	v_mfma_f32_16x16x32_bf16 v[220:223], v[68:71], v[28:31], 0
	v_mfma_f32_16x16x32_bf16 v[68:71], v[68:71], v[48:51], 0
	s_nop 5
	s_nop 7
	v_permlane16_swap_b32_e32 v192, v196
	v_permlane16_swap_b32_e32 v193, v197
	v_permlane16_swap_b32_e32 v194, v198
	v_permlane16_swap_b32_e32 v195, v199
	v_permlane16_swap_b32_e32 v200, v204
	v_permlane16_swap_b32_e32 v201, v205
	v_permlane16_swap_b32_e32 v202, v206
	v_permlane16_swap_b32_e32 v203, v207
	v_permlane16_swap_b32_e32 v208, v212
	v_permlane16_swap_b32_e32 v209, v213
	v_permlane16_swap_b32_e32 v210, v214
	v_permlane16_swap_b32_e32 v211, v215
	v_permlane16_swap_b32_e32 v216, v220
	v_permlane16_swap_b32_e32 v217, v221
	v_permlane16_swap_b32_e32 v218, v222
	v_permlane16_swap_b32_e32 v219, v223
	v_permlane32_swap_b32_e32 v192, v200
	v_permlane32_swap_b32_e32 v193, v201
	v_permlane32_swap_b32_e32 v194, v202
	v_permlane32_swap_b32_e32 v195, v203
	v_permlane32_swap_b32_e32 v196, v204
	v_permlane32_swap_b32_e32 v197, v205
	v_permlane32_swap_b32_e32 v198, v206
	v_permlane32_swap_b32_e32 v199, v207
	v_permlane32_swap_b32_e32 v208, v216
	v_permlane32_swap_b32_e32 v209, v217
	v_permlane32_swap_b32_e32 v210, v218
	v_permlane32_swap_b32_e32 v211, v219
	v_permlane32_swap_b32_e32 v212, v220
	v_permlane32_swap_b32_e32 v213, v221
	v_permlane32_swap_b32_e32 v214, v222
	v_permlane32_swap_b32_e32 v215, v223
	v_fma_f32 v242, -v132, v241, v192
	v_fma_f32 v243, v132, v240, v208
	v_fma_f32 v244, v128, v240, v242
	v_fma_f32 v245, v128, v241, v243
	v_cvt_pk_bf16_f32 v248, v244, v245
	ds_write_b32 v149, v248 offset:10240
	v_pk_mul_f32 v[232:233], v[72:73], v[224:225]
	v_pk_mul_f32 v[234:235], v[74:75], v[224:225]
	v_fma_f32 v242, -v132, v245, v193
	v_fma_f32 v243, v132, v244, v209
	v_fma_f32 v246, v128, v244, v242
	v_fma_f32 v247, v128, v245, v243
	v_cvt_pk_bf16_f32 v249, v246, v247
	ds_write_b32 v149, v249 offset:10512
	v_pk_fma_f32 v[232:233], v[72:73], v[232:233], v[226:227]
	v_pk_fma_f32 v[234:235], v[74:75], v[234:235], v[226:227]
	v_fma_f32 v242, -v132, v247, v194
	v_fma_f32 v243, v132, v246, v210
	v_fma_f32 v244, v128, v246, v242
	v_fma_f32 v245, v128, v247, v243
	v_cvt_pk_bf16_f32 v248, v244, v245
	ds_write_b32 v149, v248 offset:10784
	v_pk_mul_f32 v[232:233], v[72:73], v[232:233]
	v_pk_mul_f32 v[234:235], v[74:75], v[234:235]
	v_fma_f32 v242, -v132, v245, v195
	v_fma_f32 v243, v132, v244, v211
	v_fma_f32 v246, v128, v244, v242
	v_fma_f32 v247, v128, v245, v243
	v_cvt_pk_bf16_f32 v249, v246, v247
	ds_write_b32 v149, v249 offset:11056
	v_pk_mul_f32 v[232:233], v[232:233], v[228:229]
	v_pk_mul_f32 v[234:235], v[234:235], v[228:229]
	v_fma_f32 v242, -v132, v247, v196
	v_fma_f32 v243, v132, v246, v212
	v_fma_f32 v244, v128, v246, v242
	v_fma_f32 v245, v128, v247, v243
	v_cvt_pk_bf16_f32 v248, v244, v245
	ds_write_b32 v149, v248 offset:11328
	v_exp_f32_e32 v232, v232
	v_exp_f32_e32 v233, v233
	v_fma_f32 v242, -v132, v245, v197
	v_fma_f32 v243, v132, v244, v213
	v_fma_f32 v246, v128, v244, v242
	v_fma_f32 v247, v128, v245, v243
	v_cvt_pk_bf16_f32 v249, v246, v247
	ds_write_b32 v149, v249 offset:11600
	v_exp_f32_e32 v234, v234
	v_exp_f32_e32 v235, v235
	v_fma_f32 v242, -v132, v247, v198
	v_fma_f32 v243, v132, v246, v214
	v_fma_f32 v244, v128, v246, v242
	v_fma_f32 v245, v128, v247, v243
	v_cvt_pk_bf16_f32 v248, v244, v245
	ds_write_b32 v149, v248 offset:11872
	v_pk_add_f32 v[232:233], v[232:233], v[230:231]
	v_pk_add_f32 v[234:235], v[234:235], v[230:231]
	v_fma_f32 v242, -v132, v245, v199
	v_fma_f32 v243, v132, v244, v215
	v_fma_f32 v246, v128, v244, v242
	v_fma_f32 v247, v128, v245, v243
	v_cvt_pk_bf16_f32 v249, v246, v247
	ds_write_b32 v149, v249 offset:12144
	v_rcp_f32_e32 v232, v232
	v_rcp_f32_e32 v233, v233
	v_fma_f32 v242, -v132, v247, v200
	v_fma_f32 v243, v132, v246, v216
	v_fma_f32 v244, v128, v246, v242
	v_fma_f32 v245, v128, v247, v243
	v_cvt_pk_bf16_f32 v248, v244, v245
	ds_write_b32 v149, v248 offset:12416
	v_rcp_f32_e32 v234, v234
	v_rcp_f32_e32 v235, v235
	v_fma_f32 v242, -v132, v245, v201
	v_fma_f32 v243, v132, v244, v217
	v_fma_f32 v246, v128, v244, v242
	v_fma_f32 v247, v128, v245, v243
	v_cvt_pk_bf16_f32 v249, v246, v247
	ds_write_b32 v149, v249 offset:12688
	v_pk_mul_f32 v[232:233], v[72:73], v[232:233]
	v_pk_mul_f32 v[234:235], v[74:75], v[234:235]
	v_fma_f32 v242, -v132, v247, v202
	v_fma_f32 v243, v132, v246, v218
	v_fma_f32 v244, v128, v246, v242
	v_fma_f32 v245, v128, v247, v243
	v_cvt_pk_bf16_f32 v248, v244, v245
	ds_write_b32 v149, v248 offset:12960
	v_cvt_pk_bf16_f32 v236, v232, v232
	v_cvt_pk_bf16_f32 v237, v233, v233
	v_fma_f32 v242, -v132, v245, v203
	v_fma_f32 v243, v132, v244, v219
	v_fma_f32 v246, v128, v244, v242
	v_fma_f32 v247, v128, v245, v243
	v_cvt_pk_bf16_f32 v249, v246, v247
	ds_write_b32 v149, v249 offset:13232
	v_cvt_pk_bf16_f32 v238, v234, v234
	v_cvt_pk_bf16_f32 v239, v235, v235
	v_fma_f32 v242, -v132, v247, v204
	v_fma_f32 v243, v132, v246, v220
	v_fma_f32 v244, v128, v246, v242
	v_fma_f32 v245, v128, v247, v243
	v_cvt_pk_bf16_f32 v248, v244, v245
	ds_write_b32 v149, v248 offset:13504
	ds_write_b16 v160, v236 offset:15616
	ds_write_b16 v160, v237 offset:15648
	v_fma_f32 v242, -v132, v245, v205
	v_fma_f32 v243, v132, v244, v221
	v_fma_f32 v246, v128, v244, v242
	v_fma_f32 v247, v128, v245, v243
	v_cvt_pk_bf16_f32 v249, v246, v247
	ds_write_b32 v149, v249 offset:13776
	ds_write_b16 v160, v238 offset:15680
	ds_write_b16 v163, v239 offset:14592
	v_fma_f32 v242, -v132, v247, v206
	v_fma_f32 v243, v132, v246, v222
	v_fma_f32 v244, v128, v246, v242
	v_fma_f32 v245, v128, v247, v243
	v_cvt_pk_bf16_f32 v248, v244, v245
	ds_write_b32 v149, v248 offset:14048
	v_fma_f32 v242, -v132, v245, v207
	v_fma_f32 v243, v132, v244, v223
	v_fma_f32 v86, v128, v244, v242
	v_fma_f32 v87, v128, v245, v243
	v_cvt_pk_bf16_f32 v249, v86, v87
	ds_write_b32 v149, v249 offset:14320
	s_waitcnt lgkmcnt(0)
	ds_read_b128 v[72:75], v80 offset:10240
	ds_read_b128 v[76:79], v80 offset:10304
	ds_read_b128 v[184:187], v80 offset:10368
	ds_read_b128 v[188:191], v80 offset:10432
	s_waitcnt lgkmcnt(3)
	v_mfma_f32_16x16x32_bf16 v[68:71], v[72:75], v[32:35], v[68:71]
	s_waitcnt lgkmcnt(2)
	v_mfma_f32_16x16x32_bf16 v[68:71], v[76:79], v[36:39], v[68:71]
	s_waitcnt vmcnt(3)
	v_mov_b64_e32 v[82:83], v[54:55]
	v_mov_b64_e32 v[80:81], v[52:53]
	s_waitcnt lgkmcnt(1)
	v_mfma_f32_16x16x32_bf16 v[68:71], v[184:187], v[40:43], v[68:71]
	s_waitcnt lgkmcnt(0)
	v_mfma_f32_16x16x32_bf16 v[68:71], v[188:191], v[44:47], v[68:71]
	s_waitcnt vmcnt(2)
	v_mov_b64_e32 v[78:79], v[58:59]
	v_mov_b64_e32 v[76:77], v[56:57]
	s_nop 4
	v_pk_mul_f32 v[232:233], v[68:69], v[224:225]
	v_pk_mul_f32 v[234:235], v[70:71], v[224:225]
	v_pk_fma_f32 v[232:233], v[68:69], v[232:233], v[226:227]
	v_pk_fma_f32 v[234:235], v[70:71], v[234:235], v[226:227]
	v_pk_mul_f32 v[232:233], v[68:69], v[232:233]
	v_pk_mul_f32 v[234:235], v[70:71], v[234:235]
	v_pk_mul_f32 v[232:233], v[232:233], v[228:229]
	v_pk_mul_f32 v[234:235], v[234:235], v[228:229]
	v_exp_f32_e32 v232, v232
	v_exp_f32_e32 v233, v233
	v_exp_f32_e32 v234, v234
	v_exp_f32_e32 v235, v235
	v_pk_add_f32 v[232:233], v[232:233], v[230:231]
	v_pk_add_f32 v[234:235], v[234:235], v[230:231]
	v_rcp_f32_e32 v232, v232
	v_rcp_f32_e32 v233, v233
	v_rcp_f32_e32 v234, v234
	v_rcp_f32_e32 v235, v235
	v_pk_mul_f32 v[232:233], v[68:69], v[232:233]
	v_pk_mul_f32 v[234:235], v[70:71], v[234:235]
	v_cvt_pk_bf16_f32 v236, v232, v232
	v_cvt_pk_bf16_f32 v237, v233, v233
	v_cvt_pk_bf16_f32 v238, v234, v234
	v_cvt_pk_bf16_f32 v239, v235, v235
	ds_write_b16 v160, v236 offset:16128
	ds_write_b16 v160, v237 offset:16160
	ds_write_b16 v160, v238 offset:16192
	ds_write_b16 v164, v239 offset:14592
	s_waitcnt vmcnt(1)
	v_mov_b64_e32 v[74:75], v[62:63]
	v_mov_b64_e32 v[72:73], v[60:61]
	s_waitcnt lgkmcnt(0)
	s_waitcnt vmcnt(0)
	v_mov_b64_e32 v[70:71], v[66:67]
	v_mov_b64_e32 v[68:69], v[64:65]
